# grid barrier release side flattened: non-leader workgroups poll the top generation word directly (one hop less)
# speedup vs baseline: 1.0049x; 1.0049x over previous
; __device__ __forceinline__ unsigned xb_ld(unsigned* p)              { return __hip_atomic_load(p, __ATOMIC_RELAXED, __HIP_MEMORY_SCOPE_AGENT); }
; __device__ __forceinline__ unsigned xb_add(unsigned* p, unsigned v) { return __hip_atomic_fetch_add(p, v, __ATOMIC_RELAXED, __HIP_MEMORY_SCOPE_AGENT); }
; #define XB_SPIN(cond, bar) do { unsigned _sp = 0; while (cond) { __builtin_amdgcn_s_sleep(1); \
;     if ((++_sp & 255u) == 0u) { if (xb_ld(&(bar)[XB_TMO])) break; if (_sp > XB_SPIN_CAP) { atomicAdd(&(bar)[XB_TMO], 1u); break; } } } } while (0)
; __device__ __forceinline__ void xcd_barrier(const XcdBarrier& b) {
;     ...
;         const unsigned old = xb_add(&bar[XB_XSUB(b.x)], 1u);
;         const unsigned gen = old / nloc;
;         if (old + 1u == (gen + 1u) * nloc) {
;             __builtin_amdgcn_fence(__ATOMIC_RELEASE, "agent");
;             asm volatile("s_waitcnt vmcnt(0)" ::: "memory");
;             const unsigned og = xb_add(&bar[XB_TOP], 1u);
;             const unsigned tg = og / nx;
;             if (og + 1u == (tg + 1u) * nx) xb_add(&bar[XB_TOPGEN], 1u);
;             else XB_SPIN(xb_ld(&bar[XB_TOPGEN]) == tg, bar);
;             __builtin_amdgcn_fence(__ATOMIC_ACQUIRE, "agent");
;             xb_add(&bar[XB_XGEN(b.x)], 1u);
;             asm volatile("s_waitcnt vmcnt(0)" ::: "memory");
;         } else {
;             XB_SPIN(xb_ld(&bar[XB_XGEN(b.x)]) == gen, bar);
.LBB0_46:
	s_or_b64 exec, exec, s[38:39]
	v_cvt_f32_u32_e32 v4, v2
	s_waitcnt vmcnt(0)
	v_readfirstlane_b32 s29, v3
	v_sub_u32_e32 v3, 0, v2
	v_rcp_iflag_f32_e32 v4, v4
	v_add_u32_e32 v5, s29, v1
	v_mul_f32_e32 v4, 0x4f7ffffe, v4
	v_cvt_u32_f32_e32 v4, v4
	v_mul_lo_u32 v1, v3, v4
	v_mul_hi_u32 v1, v4, v1
	v_add_u32_e32 v1, v4, v1
	v_mul_hi_u32 v1, v5, v1
	v_mul_lo_u32 v3, v1, v2
	v_sub_u32_e32 v3, v5, v3
	v_add_u32_e32 v4, 1, v1
	v_cmp_ge_u32_e32 vcc, v3, v2
	s_nop 1
	v_cndmask_b32_e32 v1, v1, v4, vcc
	v_sub_u32_e32 v4, v3, v2
	v_cndmask_b32_e32 v3, v3, v4, vcc
	v_add_u32_e32 v4, 1, v1
	v_cmp_ge_u32_e32 vcc, v3, v2
	v_add_u32_e32 v3, 1, v5
	s_nop 0
	v_cndmask_b32_e32 v1, v1, v4, vcc
	v_mul_lo_u32 v4, v2, v1
	v_add_u32_e32 v2, v4, v2
	v_cmp_ne_u32_e32 vcc, v3, v2
	s_and_saveexec_b64 s[34:35], vcc
	s_xor_b64 s[38:39], exec, s[34:35]
	s_cbranch_execz .LBB0_60
	v_readlane_b32 s34, v252, 42
	v_readlane_b32 s35, v252, 43
	s_waitcnt lgkmcnt(0)
	s_nop 3
	global_load_dword v0, v65, s[34:35] sc1
	s_waitcnt vmcnt(0)
	v_cmp_eq_u32_e32 vcc, v0, v1
	s_and_saveexec_b64 s[42:43], vcc
	s_cbranch_execz .LBB0_59
	s_mov_b32 s29, 1
	s_mov_b64 s[44:45], 0
	s_branch .LBB0_50

; __device__ __forceinline__ unsigned xb_ld(unsigned* p)              { return __hip_atomic_load(p, __ATOMIC_RELAXED, __HIP_MEMORY_SCOPE_AGENT); }
; #define XB_SPIN(cond, bar) do { unsigned _sp = 0; while (cond) { __builtin_amdgcn_s_sleep(1); \
;     if ((++_sp & 255u) == 0u) { if (xb_ld(&(bar)[XB_TMO])) break; if (_sp > XB_SPIN_CAP) { atomicAdd(&(bar)[XB_TMO], 1u); break; } } } } while (0)
; __device__ __forceinline__ void xcd_barrier(const XcdBarrier& b) {
;     ...
;         } else {
;             XB_SPIN(xb_ld(&bar[XB_XGEN(b.x)]) == gen, bar);
.LBB0_52:
	v_readlane_b32 s34, v252, 42
	v_readlane_b32 s35, v252, 43
	s_add_i32 s29, s29, 1
	s_mov_b64 s[50:51], -1
	s_nop 2
	global_load_dword v0, v65, s[34:35] sc1
	s_waitcnt vmcnt(0)
	v_cmp_ne_u32_e32 vcc, v0, v1
	s_orn2_b64 s[48:49], vcc, exec
	s_branch .LBB0_49

; __device__ __forceinline__ unsigned xb_ld(unsigned* p)              { return __hip_atomic_load(p, __ATOMIC_RELAXED, __HIP_MEMORY_SCOPE_AGENT); }
; __device__ __forceinline__ unsigned xb_add(unsigned* p, unsigned v) { return __hip_atomic_fetch_add(p, v, __ATOMIC_RELAXED, __HIP_MEMORY_SCOPE_AGENT); }
; #define XB_SPIN(cond, bar) do { unsigned _sp = 0; while (cond) { __builtin_amdgcn_s_sleep(1); \
;     if ((++_sp & 255u) == 0u) { if (xb_ld(&(bar)[XB_TMO])) break; if (_sp > XB_SPIN_CAP) { atomicAdd(&(bar)[XB_TMO], 1u); break; } } } } while (0)
; __device__ __forceinline__ void xcd_barrier(const XcdBarrier& b) {
;     ...
;         const unsigned old = xb_add(&bar[XB_XSUB(b.x)], 1u);
;         const unsigned gen = old / nloc;
;         if (old + 1u == (gen + 1u) * nloc) {
;             __builtin_amdgcn_fence(__ATOMIC_RELEASE, "agent");
;             asm volatile("s_waitcnt vmcnt(0)" ::: "memory");
;             const unsigned og = xb_add(&bar[XB_TOP], 1u);
;             const unsigned tg = og / nx;
;             if (og + 1u == (tg + 1u) * nx) xb_add(&bar[XB_TOPGEN], 1u);
;             else XB_SPIN(xb_ld(&bar[XB_TOPGEN]) == tg, bar);
;             __builtin_amdgcn_fence(__ATOMIC_ACQUIRE, "agent");
;             xb_add(&bar[XB_XGEN(b.x)], 1u);
;             asm volatile("s_waitcnt vmcnt(0)" ::: "memory");
;         } else {
;             XB_SPIN(xb_ld(&bar[XB_XGEN(b.x)]) == gen, bar);
.LBB0_1396:
	s_or_b64 exec, exec, s[40:41]
	v_cvt_f32_u32_e32 v4, v2
	s_waitcnt vmcnt(0)
	v_readfirstlane_b32 s29, v3
	v_sub_u32_e32 v3, 0, v2
	v_rcp_iflag_f32_e32 v4, v4
	v_add_u32_e32 v5, s29, v1
	v_mul_f32_e32 v4, 0x4f7ffffe, v4
	v_cvt_u32_f32_e32 v4, v4
	v_mul_lo_u32 v1, v3, v4
	v_mul_hi_u32 v1, v4, v1
	v_add_u32_e32 v1, v4, v1
	v_mul_hi_u32 v1, v5, v1
	v_mul_lo_u32 v3, v1, v2
	v_sub_u32_e32 v3, v5, v3
	v_add_u32_e32 v4, 1, v1
	v_cmp_ge_u32_e32 vcc, v3, v2
	s_nop 1
	v_cndmask_b32_e32 v1, v1, v4, vcc
	v_sub_u32_e32 v4, v3, v2
	v_cndmask_b32_e32 v3, v3, v4, vcc
	v_add_u32_e32 v4, 1, v1
	v_cmp_ge_u32_e32 vcc, v3, v2
	v_add_u32_e32 v3, 1, v5
	s_nop 0
	v_cndmask_b32_e32 v1, v1, v4, vcc
	v_mul_lo_u32 v4, v2, v1
	v_add_u32_e32 v2, v4, v2
	v_cmp_ne_u32_e32 vcc, v3, v2
	s_and_saveexec_b64 s[34:35], vcc
	s_xor_b64 s[40:41], exec, s[34:35]
	s_cbranch_execz .LBB0_1410
	v_readlane_b32 s34, v252, 42
	v_readlane_b32 s35, v252, 43
	s_waitcnt lgkmcnt(0)
	s_nop 3
	global_load_dword v0, v65, s[34:35] sc1
	s_waitcnt vmcnt(0)
	v_cmp_eq_u32_e32 vcc, v0, v1
	s_and_saveexec_b64 s[42:43], vcc
	s_cbranch_execz .LBB0_1409
	s_mov_b32 s29, 1
	s_mov_b64 s[44:45], 0
	s_branch .LBB0_1400

; __device__ __forceinline__ unsigned xb_ld(unsigned* p)              { return __hip_atomic_load(p, __ATOMIC_RELAXED, __HIP_MEMORY_SCOPE_AGENT); }
; __device__ __forceinline__ unsigned xb_add(unsigned* p, unsigned v) { return __hip_atomic_fetch_add(p, v, __ATOMIC_RELAXED, __HIP_MEMORY_SCOPE_AGENT); }
; #define XB_SPIN(cond, bar) do { unsigned _sp = 0; while (cond) { __builtin_amdgcn_s_sleep(1); \
;     if ((++_sp & 255u) == 0u) { if (xb_ld(&(bar)[XB_TMO])) break; if (_sp > XB_SPIN_CAP) { atomicAdd(&(bar)[XB_TMO], 1u); break; } } } } while (0)
; __device__ __forceinline__ void xcd_barrier(const XcdBarrier& b) {
;     ...
;         const unsigned old = xb_add(&bar[XB_XSUB(b.x)], 1u);
;         const unsigned gen = old / nloc;
;         if (old + 1u == (gen + 1u) * nloc) {
;             __builtin_amdgcn_fence(__ATOMIC_RELEASE, "agent");
;             asm volatile("s_waitcnt vmcnt(0)" ::: "memory");
;             const unsigned og = xb_add(&bar[XB_TOP], 1u);
;             const unsigned tg = og / nx;
;             if (og + 1u == (tg + 1u) * nx) xb_add(&bar[XB_TOPGEN], 1u);
;             else XB_SPIN(xb_ld(&bar[XB_TOPGEN]) == tg, bar);
;             __builtin_amdgcn_fence(__ATOMIC_ACQUIRE, "agent");
;             xb_add(&bar[XB_XGEN(b.x)], 1u);
;             asm volatile("s_waitcnt vmcnt(0)" ::: "memory");
;         } else {
;             XB_SPIN(xb_ld(&bar[XB_XGEN(b.x)]) == gen, bar);
.LBB0_1451:
	s_or_b64 exec, exec, s[38:39]
	v_cvt_f32_u32_e32 v4, v2
	s_waitcnt vmcnt(0)
	v_readfirstlane_b32 s29, v3
	v_sub_u32_e32 v3, 0, v2
	v_rcp_iflag_f32_e32 v4, v4
	v_add_u32_e32 v5, s29, v1
	v_mul_f32_e32 v4, 0x4f7ffffe, v4
	v_cvt_u32_f32_e32 v4, v4
	v_mul_lo_u32 v1, v3, v4
	v_mul_hi_u32 v1, v4, v1
	v_add_u32_e32 v1, v4, v1
	v_mul_hi_u32 v1, v5, v1
	v_mul_lo_u32 v3, v1, v2
	v_sub_u32_e32 v3, v5, v3
	v_add_u32_e32 v4, 1, v1
	v_cmp_ge_u32_e32 vcc, v3, v2
	s_nop 1
	v_cndmask_b32_e32 v1, v1, v4, vcc
	v_sub_u32_e32 v4, v3, v2
	v_cndmask_b32_e32 v3, v3, v4, vcc
	v_add_u32_e32 v4, 1, v1
	v_cmp_ge_u32_e32 vcc, v3, v2
	v_add_u32_e32 v3, 1, v5
	s_nop 0
	v_cndmask_b32_e32 v1, v1, v4, vcc
	v_mul_lo_u32 v4, v2, v1
	v_add_u32_e32 v2, v4, v2
	v_cmp_ne_u32_e32 vcc, v3, v2
	s_and_saveexec_b64 s[34:35], vcc
	s_xor_b64 s[38:39], exec, s[34:35]
	s_cbranch_execz .LBB0_1465
	v_readlane_b32 s34, v252, 42
	v_readlane_b32 s35, v252, 43
	s_waitcnt lgkmcnt(0)
	s_nop 3
	global_load_dword v0, v65, s[34:35] sc1
	s_waitcnt vmcnt(0)
	v_cmp_eq_u32_e32 vcc, v0, v1
	s_and_saveexec_b64 s[40:41], vcc
	s_cbranch_execz .LBB0_1464
	s_mov_b32 s29, 1
	s_mov_b64 s[42:43], 0
	s_branch .LBB0_1455

; __device__ __forceinline__ unsigned xb_ld(unsigned* p)              { return __hip_atomic_load(p, __ATOMIC_RELAXED, __HIP_MEMORY_SCOPE_AGENT); }
; #define XB_SPIN(cond, bar) do { unsigned _sp = 0; while (cond) { __builtin_amdgcn_s_sleep(1); \
;     if ((++_sp & 255u) == 0u) { if (xb_ld(&(bar)[XB_TMO])) break; if (_sp > XB_SPIN_CAP) { atomicAdd(&(bar)[XB_TMO], 1u); break; } } } } while (0)
; __device__ __forceinline__ void xcd_barrier(const XcdBarrier& b) {
;     ...
;         } else {
;             XB_SPIN(xb_ld(&bar[XB_XGEN(b.x)]) == gen, bar);
.LBB0_1457:
	v_readlane_b32 s34, v252, 42
	v_readlane_b32 s35, v252, 43
	s_add_i32 s29, s29, 1
	s_mov_b64 s[48:49], -1
	s_nop 2
	global_load_dword v0, v65, s[34:35] sc1
	s_waitcnt vmcnt(0)
	v_cmp_ne_u32_e32 vcc, v0, v1
	s_orn2_b64 s[46:47], vcc, exec
	s_branch .LBB0_1454
